# group barriers poll with two flag-block reads in flight (no sleep), flag store waited
# baseline (speedup 1.0000x reference)
.Lxb0_noinv:
	s_and_saveexec_b64 s[2:3], s[4:5]
	s_cbranch_execz .LBB0_246
	s_waitcnt vmcnt(0) lgkmcnt(0)
	v_readlane_b32 s20, v162, 62
	v_readlane_b32 s21, v164, 0
	v_readlane_b32 s22, v162, 63
	s_cmp_eq_u32 s20, 1
	s_cbranch_scc0 .Lxb0_glob
	s_and_b32 s4, s21, 15
	s_lshl_b32 s4, s4, 8
	s_bfe_u32 s5, s21, 0x20004
	s_lshl_b32 s5, s5, 5
	s_add_u32 s4, s4, s5
	s_add_u32 s4, s4, 0x480
	s_add_u32 s4, s84, s4
	s_addc_u32 s5, s85, 0
	s_add_u32 s22, s22, 1
	s_nop 1
	v_writelane_b32 v162, s22, 63
	s_lshr_b32 s21, s21, 6
	s_lshl_b32 s21, s21, 2
	v_mov_b32_e32 v5, s21
	v_mov_b32_e32 v6, s22
	global_store_dword v5, v6, s[4:5]
	s_waitcnt vmcnt(0)
	s_mov_b32 s20, 0
	global_load_dwordx4 v[8:11], v117, s[4:5] sc1
	global_load_dwordx4 v[12:15], v117, s[4:5] offset:16 sc1
.Lxb0_gspin:
	global_load_dwordx4 v[0:3], v117, s[4:5] sc1
	global_load_dwordx4 v[4:7], v117, s[4:5] offset:16 sc1
	s_waitcnt vmcnt(2)
	v_min_u32_e32 v8, v8, v9
	v_min_u32_e32 v10, v10, v11
	v_min_u32_e32 v12, v12, v13
	v_min_u32_e32 v14, v14, v15
	v_min_u32_e32 v8, v8, v10
	v_min_u32_e32 v12, v12, v14
	s_nop 0
	v_min_u32_e32 v8, v8, v12
	s_nop 0
	v_readfirstlane_b32 s21, v8
	s_cmp_ge_u32 s21, s22
	s_cbranch_scc1 .Lxb0_done
	global_load_dwordx4 v[8:11], v117, s[4:5] sc1
	global_load_dwordx4 v[12:15], v117, s[4:5] offset:16 sc1
	s_waitcnt vmcnt(2)
	v_min_u32_e32 v0, v0, v1
	v_min_u32_e32 v2, v2, v3
	v_min_u32_e32 v4, v4, v5
	v_min_u32_e32 v6, v6, v7
	v_min_u32_e32 v0, v0, v2
	v_min_u32_e32 v4, v4, v6
	s_nop 0
	v_min_u32_e32 v0, v0, v4
	s_nop 0
	v_readfirstlane_b32 s21, v0
	s_cmp_ge_u32 s21, s22
	s_cbranch_scc1 .Lxb0_done
	s_add_u32 s20, s20, 1
	s_cmp_lt_u32 s20, 0x10000
	s_cbranch_scc1 .Lxb0_gspin
	s_branch .Lxb0_done

.LBB0_1123:
	s_waitcnt vmcnt(0) lgkmcnt(0)
	v_readlane_b32 s20, v162, 62
	v_readlane_b32 s21, v164, 0
	v_readlane_b32 s22, v162, 63
	s_cmp_eq_u32 s20, 1
	s_cbranch_scc0 .Lxb11_glob
	s_and_b32 s4, s21, 15
	s_lshl_b32 s4, s4, 8
	s_bfe_u32 s5, s21, 0x20004
	s_lshl_b32 s5, s5, 5
	s_add_u32 s4, s4, s5
	s_add_u32 s4, s4, 0x480
	s_add_u32 s4, s84, s4
	s_addc_u32 s5, s85, 0
	s_add_u32 s22, s22, 1
	s_nop 1
	v_writelane_b32 v162, s22, 63
	s_lshr_b32 s21, s21, 6
	s_lshl_b32 s21, s21, 2
	v_mov_b32_e32 v5, s21
	v_mov_b32_e32 v6, s22
	global_store_dword v5, v6, s[4:5]
	s_waitcnt vmcnt(0)
	s_mov_b32 s20, 0
	global_load_dwordx4 v[8:11], v117, s[4:5] sc1
	global_load_dwordx4 v[12:15], v117, s[4:5] offset:16 sc1
